# v13_gmlp
# baseline (speedup 1.0000x reference)
; __device__ __forceinline__ u16 f2bf(float f) { return (u16)pack2(f, f); }
; __device__ __forceinline__ float bf2f(u16 h) { return __uint_as_float(((unsigned)h) << 16); }
; __device__ void gmlp_item(const Params& P, int item, u16* shm, int wid_s) {
;     ...
; #pragma unroll
;     for (int nt = 0; nt < 8; ++nt)
; #pragma unroll
;       for (int j = 0; j < 4; ++j) {
;         int i = wid * 16 + fq * 4 + j, c = nt * 16 + fr, row = row0 + i;
;         float mixed = P.gz[g * 128 + c] * acc[nt][j] + P.gbs[g * 128 + i];
;         float u = bf2f(WSU(UB)[(size_t)row * SBW + g * 128 + c]);
;         WSU(OB)[(size_t)row * DM + SBW + g * 128 + c] = f2bf(u * mixed);
;       }
.LBB0_142:
	s_or_b64 exec, exec, s[4:5]
	s_lshl_b32 s5, s20, 7
	v_lshl_or_b32 v3, v38, 2, v37
	v_or_b32_e32 v0, s5, v36
	s_lshl_b32 s4, s20, 8
	v_readlane_b32 s6, v230, 42
	v_lshlrev_b32_e32 v44, 2, v0
	v_lshlrev_b32_e32 v0, 1, v36
	v_add_u32_e32 v36, s5, v3
	v_readlane_b32 s36, v231, 32
	v_readlane_b32 s7, v230, 43
	s_add_u32 s6, s6, s4
	v_add_u32_e32 v2, s17, v3
	v_ashrrev_i32_e32 v37, 31, v36
	v_readlane_b32 s48, v231, 44
	v_readlane_b32 s49, v231, 45
	s_addc_u32 s7, s7, 0
	v_ashrrev_i32_e32 v3, 31, v2
	v_lshl_add_u64 v[36:37], v[36:37], 2, s[48:49]
	v_lshl_add_u64 v[40:41], s[6:7], 0, v[0:1]
	v_readlane_b32 s44, v231, 40
	v_readlane_b32 s45, v231, 41
	global_load_dwordx4 v[36:39], v[36:37], off
	v_lshlrev_b64 v[42:43], 11, v[2:3]
	v_lshl_add_u64 v[42:43], v[40:41], 0, v[42:43]
	s_nop 1
	global_load_dword v50, v44, s[44:45]
	global_load_dword v51, v44, s[44:45] offset:64
	global_load_dword v52, v44, s[44:45] offset:128
	global_load_dword v53, v44, s[44:45] offset:192
	global_load_dword v54, v44, s[44:45] offset:256
	global_load_dword v55, v44, s[44:45] offset:320
	global_load_dword v56, v44, s[44:45] offset:384
	global_load_dword v57, v44, s[44:45] offset:448
	s_add_u32 s4, s54, s4
	s_addc_u32 s5, s65, 0
	v_readlane_b32 s37, v231, 33
	v_readlane_b32 s38, v231, 34
	v_readlane_b32 s39, v231, 35
	v_readlane_b32 s40, v231, 36
	v_readlane_b32 s41, v231, 37
	v_readlane_b32 s42, v231, 38
	v_readlane_b32 s43, v231, 39
	v_readlane_b32 s46, v231, 42
	v_readlane_b32 s47, v231, 43
	v_readlane_b32 s50, v231, 46
	v_readlane_b32 s51, v231, 47
	s_mov_b64 s[6:7], 0x1000
	v_lshlrev_b64 v[66:67], 11, v[2:3]
	v_lshlrev_b64 v[70:71], 12, v[2:3]
	v_lshl_add_u64 v[68:69], s[4:5], 0, v[0:1]
	v_lshl_add_u64 v[66:67], v[40:41], 0, v[66:67]
	v_lshl_add_u64 v[68:69], v[68:69], 0, v[70:71]
	v_lshl_add_u64 v[72:73], v[66:67], 0, s[6:7]
	v_lshl_add_u64 v[106:107], v[68:69], 0, s[6:7]
	global_load_ushort v74, v[66:67], off
	global_load_ushort v75, v[66:67], off offset:32
	global_load_ushort v76, v[66:67], off offset:64
	global_load_ushort v77, v[66:67], off offset:96
	global_load_ushort v78, v[66:67], off offset:128
	global_load_ushort v79, v[66:67], off offset:160
	global_load_ushort v80, v[66:67], off offset:192
	global_load_ushort v81, v[66:67], off offset:224
	global_load_ushort v82, v[66:67], off offset:2048
	global_load_ushort v83, v[66:67], off offset:2080
	global_load_ushort v84, v[66:67], off offset:2112
	global_load_ushort v85, v[66:67], off offset:2144
	global_load_ushort v86, v[66:67], off offset:2176
	global_load_ushort v87, v[66:67], off offset:2208
	global_load_ushort v88, v[66:67], off offset:2240
	global_load_ushort v89, v[66:67], off offset:2272
	global_load_ushort v90, v[72:73], off
	global_load_ushort v91, v[72:73], off offset:32
	global_load_ushort v92, v[72:73], off offset:64
	global_load_ushort v93, v[72:73], off offset:96
	global_load_ushort v94, v[72:73], off offset:128
	global_load_ushort v95, v[72:73], off offset:160
	global_load_ushort v96, v[72:73], off offset:192
	global_load_ushort v97, v[72:73], off offset:224
	global_load_ushort v98, v[72:73], off offset:2048
	global_load_ushort v99, v[72:73], off offset:2080
	global_load_ushort v100, v[72:73], off offset:2112
	global_load_ushort v101, v[72:73], off offset:2144
	global_load_ushort v102, v[72:73], off offset:2176
	global_load_ushort v103, v[72:73], off offset:2208
	global_load_ushort v104, v[72:73], off offset:2240
	global_load_ushort v105, v[72:73], off offset:2272
	v_lshl_add_u64 v[108:109], v[106:107], 0, s[6:7]
	v_lshl_add_u64 v[110:111], v[108:109], 0, s[6:7]
	s_waitcnt vmcnt(24)
	v_fma_f32 v32, v32, v50, v36
	v_fma_f32 v28, v28, v51, v36
	v_fma_f32 v24, v24, v52, v36
	v_fma_f32 v20, v20, v53, v36
	v_fma_f32 v16, v16, v54, v36
	v_fma_f32 v12, v12, v55, v36
	v_fma_f32 v8, v8, v56, v36
	v_fma_f32 v4, v4, v57, v36
	v_lshlrev_b32_e32 v74, 16, v74
	v_lshlrev_b32_e32 v75, 16, v75
	v_lshlrev_b32_e32 v76, 16, v76
	v_lshlrev_b32_e32 v77, 16, v77
	v_lshlrev_b32_e32 v78, 16, v78
	v_lshlrev_b32_e32 v79, 16, v79
	v_lshlrev_b32_e32 v80, 16, v80
	v_lshlrev_b32_e32 v81, 16, v81
	v_mul_f32_e32 v32, v32, v74
	v_mul_f32_e32 v28, v28, v75
	v_mul_f32_e32 v24, v24, v76
	v_mul_f32_e32 v20, v20, v77
	v_mul_f32_e32 v16, v16, v78
	v_mul_f32_e32 v12, v12, v79
	v_mul_f32_e32 v8, v8, v80
	v_mul_f32_e32 v4, v4, v81
	v_cvt_pk_bf16_f32 v32, v32, v32
	v_cvt_pk_bf16_f32 v28, v28, v28
	v_cvt_pk_bf16_f32 v24, v24, v24
	v_cvt_pk_bf16_f32 v20, v20, v20
	v_cvt_pk_bf16_f32 v16, v16, v16
	v_cvt_pk_bf16_f32 v12, v12, v12
	v_cvt_pk_bf16_f32 v8, v8, v8
	v_cvt_pk_bf16_f32 v4, v4, v4
	global_store_short v[68:69], v32, off
	global_store_short v[68:69], v28, off offset:32
	global_store_short v[68:69], v24, off offset:64
	global_store_short v[68:69], v20, off offset:96
	global_store_short v[68:69], v16, off offset:128
	global_store_short v[68:69], v12, off offset:160
	global_store_short v[68:69], v8, off offset:192
	global_store_short v[68:69], v4, off offset:224
	s_waitcnt vmcnt(24)
; __device__ __forceinline__ u16 f2bf(float f) { return (u16)pack2(f, f); }
; __device__ __forceinline__ float bf2f(u16 h) { return __uint_as_float(((unsigned)h) << 16); }
; __device__ void gmlp_item(const Params& P, int item, u16* shm, int wid_s) {
;     ...
; #pragma unroll
;     for (int nt = 0; nt < 8; ++nt)
; #pragma unroll
;       for (int j = 0; j < 4; ++j) {
;         int i = wid * 16 + fq * 4 + j, c = nt * 16 + fr, row = row0 + i;
;         float mixed = P.gz[g * 128 + c] * acc[nt][j] + P.gbs[g * 128 + i];
;         float u = bf2f(WSU(UB)[(size_t)row * SBW + g * 128 + c]);
;         WSU(OB)[(size_t)row * DM + SBW + g * 128 + c] = f2bf(u * mixed);
;       }
	v_fma_f32 v33, v33, v50, v37
	v_fma_f32 v29, v29, v51, v37
	v_fma_f32 v25, v25, v52, v37
	v_fma_f32 v21, v21, v53, v37
	v_fma_f32 v17, v17, v54, v37
	v_fma_f32 v13, v13, v55, v37
	v_fma_f32 v9, v9, v56, v37
	v_fma_f32 v5, v5, v57, v37
	v_lshlrev_b32_e32 v82, 16, v82
	v_lshlrev_b32_e32 v83, 16, v83
	v_lshlrev_b32_e32 v84, 16, v84
	v_lshlrev_b32_e32 v85, 16, v85
	v_lshlrev_b32_e32 v86, 16, v86
	v_lshlrev_b32_e32 v87, 16, v87
	v_lshlrev_b32_e32 v88, 16, v88
	v_lshlrev_b32_e32 v89, 16, v89
	v_mul_f32_e32 v33, v33, v82
	v_mul_f32_e32 v29, v29, v83
	v_mul_f32_e32 v25, v25, v84
	v_mul_f32_e32 v21, v21, v85
	v_mul_f32_e32 v17, v17, v86
	v_mul_f32_e32 v13, v13, v87
	v_mul_f32_e32 v9, v9, v88
	v_mul_f32_e32 v5, v5, v89
	v_cvt_pk_bf16_f32 v33, v33, v33
	v_cvt_pk_bf16_f32 v29, v29, v29
	v_cvt_pk_bf16_f32 v25, v25, v25
	v_cvt_pk_bf16_f32 v21, v21, v21
	v_cvt_pk_bf16_f32 v17, v17, v17
	v_cvt_pk_bf16_f32 v13, v13, v13
	v_cvt_pk_bf16_f32 v9, v9, v9
	v_cvt_pk_bf16_f32 v5, v5, v5
	global_store_short v[106:107], v33, off
	global_store_short v[106:107], v29, off offset:32
	global_store_short v[106:107], v25, off offset:64
	global_store_short v[106:107], v21, off offset:96
	global_store_short v[106:107], v17, off offset:128
	global_store_short v[106:107], v13, off offset:160
	global_store_short v[106:107], v9, off offset:192
	global_store_short v[106:107], v5, off offset:224
	s_waitcnt vmcnt(24)
	v_fma_f32 v34, v34, v50, v38
	v_fma_f32 v30, v30, v51, v38
	v_fma_f32 v26, v26, v52, v38
	v_fma_f32 v22, v22, v53, v38
	v_fma_f32 v18, v18, v54, v38
	v_fma_f32 v14, v14, v55, v38
	v_fma_f32 v10, v10, v56, v38
	v_fma_f32 v6, v6, v57, v38
	v_lshlrev_b32_e32 v90, 16, v90
	v_lshlrev_b32_e32 v91, 16, v91
	v_lshlrev_b32_e32 v92, 16, v92
	v_lshlrev_b32_e32 v93, 16, v93
	v_lshlrev_b32_e32 v94, 16, v94
	v_lshlrev_b32_e32 v95, 16, v95
	v_lshlrev_b32_e32 v96, 16, v96
	v_lshlrev_b32_e32 v97, 16, v97
	v_mul_f32_e32 v34, v34, v90
	v_mul_f32_e32 v30, v30, v91
	v_mul_f32_e32 v26, v26, v92
	v_mul_f32_e32 v22, v22, v93
	v_mul_f32_e32 v18, v18, v94
	v_mul_f32_e32 v14, v14, v95
	v_mul_f32_e32 v10, v10, v96
	v_mul_f32_e32 v6, v6, v97
	v_cvt_pk_bf16_f32 v34, v34, v34
	v_cvt_pk_bf16_f32 v30, v30, v30
	v_cvt_pk_bf16_f32 v26, v26, v26
	v_cvt_pk_bf16_f32 v22, v22, v22
	v_cvt_pk_bf16_f32 v18, v18, v18
	v_cvt_pk_bf16_f32 v14, v14, v14
	v_cvt_pk_bf16_f32 v10, v10, v10
	v_cvt_pk_bf16_f32 v6, v6, v6
	global_store_short v[108:109], v34, off
	global_store_short v[108:109], v30, off offset:32
	global_store_short v[108:109], v26, off offset:64
	global_store_short v[108:109], v22, off offset:96
	global_store_short v[108:109], v18, off offset:128
	global_store_short v[108:109], v14, off offset:160
	global_store_short v[108:109], v10, off offset:192
	global_store_short v[108:109], v6, off offset:224
	s_waitcnt vmcnt(24)
	v_fma_f32 v35, v35, v50, v39
	v_fma_f32 v31, v31, v51, v39
	v_fma_f32 v27, v27, v52, v39
	v_fma_f32 v23, v23, v53, v39
	v_fma_f32 v19, v19, v54, v39
	v_fma_f32 v15, v15, v55, v39
	v_fma_f32 v11, v11, v56, v39
	v_fma_f32 v7, v7, v57, v39
	v_lshlrev_b32_e32 v98, 16, v98
	v_lshlrev_b32_e32 v99, 16, v99
	v_lshlrev_b32_e32 v100, 16, v100
	v_lshlrev_b32_e32 v101, 16, v101
	v_lshlrev_b32_e32 v102, 16, v102
	v_lshlrev_b32_e32 v103, 16, v103
	v_lshlrev_b32_e32 v104, 16, v104
	v_lshlrev_b32_e32 v105, 16, v105
	v_mul_f32_e32 v35, v35, v98
	v_mul_f32_e32 v31, v31, v99
	v_mul_f32_e32 v27, v27, v100
	v_mul_f32_e32 v23, v23, v101
	v_mul_f32_e32 v19, v19, v102
	v_mul_f32_e32 v15, v15, v103
	v_mul_f32_e32 v11, v11, v104
	v_mul_f32_e32 v7, v7, v105
	v_cvt_pk_bf16_f32 v35, v35, v35
	v_cvt_pk_bf16_f32 v31, v31, v31
	v_cvt_pk_bf16_f32 v27, v27, v27
	v_cvt_pk_bf16_f32 v23, v23, v23
	v_cvt_pk_bf16_f32 v19, v19, v19
	v_cvt_pk_bf16_f32 v15, v15, v15
	v_cvt_pk_bf16_f32 v11, v11, v11
	v_cvt_pk_bf16_f32 v7, v7, v7
	global_store_short v[110:111], v35, off
	global_store_short v[110:111], v31, off offset:32
	global_store_short v[110:111], v27, off offset:64
	global_store_short v[110:111], v23, off offset:96
	global_store_short v[110:111], v19, off offset:128
	global_store_short v[110:111], v15, off offset:160
	global_store_short v[110:111], v11, off offset:192
	global_store_short v[110:111], v7, off offset:224
